# group barrier after GEMM2: the XCC-mapping flag word is requested behind the previous barrier's arrival atomic instead of at this barrier's arrival
# baseline (speedup 1.0000x reference)
.LBB0_1240:
	s_mov_b64 s[18:19], exec
	v_mbcnt_lo_u32_b32 v1, s18, 0
	v_mbcnt_hi_u32_b32 v1, s19, v1
	v_cmp_eq_u32_e32 vcc, 0, v1
	s_and_saveexec_b64 s[16:17], vcc
	s_cbranch_execz .LBB0_1242
	s_bcnt1_i32_b64 s18, s[18:19]
	v_mov_b32_e32 v3, 0
	v_mov_b32_e32 v4, s18
	global_atomic_add v3, v3, v4, s[94:95] sc0
	buffer_inv sc1
	s_add_u32 s62, s88, 0x4000
	s_addc_u32 s63, s89, 0
	v_mov_b32_e32 v18, 0
	global_load_dword v19, v18, s[62:63] offset:3072 sc1
.LBB0_1242:
	s_or_b64 exec, exec, s[16:17]
	v_cvt_f32_u32_e32 v4, v2
	s_waitcnt vmcnt(2)
	v_readfirstlane_b32 s16, v3
	v_sub_u32_e32 v3, 0, v2
	v_rcp_iflag_f32_e32 v4, v4
	v_add_u32_e32 v5, s16, v1
	v_mul_f32_e32 v4, 0x4f7ffffe, v4
	v_cvt_u32_f32_e32 v4, v4
	v_mul_lo_u32 v1, v3, v4
	v_mul_hi_u32 v1, v4, v1
	v_add_u32_e32 v1, v4, v1
	v_mul_hi_u32 v1, v5, v1
	v_mul_lo_u32 v3, v1, v2
	v_sub_u32_e32 v3, v5, v3
	v_add_u32_e32 v4, 1, v1
	v_cmp_ge_u32_e32 vcc, v3, v2
	s_nop 1
	v_cndmask_b32_e32 v1, v1, v4, vcc
	v_sub_u32_e32 v4, v3, v2
	v_cndmask_b32_e32 v3, v3, v4, vcc
	v_add_u32_e32 v4, 1, v1
	v_cmp_ge_u32_e32 vcc, v3, v2
	v_add_u32_e32 v3, 1, v5
	s_nop 0
	v_cndmask_b32_e32 v1, v1, v4, vcc
	v_mul_lo_u32 v4, v2, v1
	v_add_u32_e32 v2, v4, v2
	v_cmp_ne_u32_e32 vcc, v3, v2
	s_and_saveexec_b64 s[16:17], vcc
	s_xor_b64 s[16:17], exec, s[16:17]
	s_cbranch_execz .LBB0_1256
	s_waitcnt lgkmcnt(0)
	v_mov_b32_e32 v0, 0
	global_load_dword v2, v0, s[14:15] sc1
	s_waitcnt vmcnt(0)
	v_cmp_eq_u32_e32 vcc, v2, v1
	s_and_saveexec_b64 s[18:19], vcc
	s_cbranch_execz .LBB0_1255
	s_mov_b32 s22, 1
	s_mov_b64 s[36:37], 0
	s_branch .LBB0_1246

.LBB0_1276:
	s_or_b64 exec, exec, s[12:13]
	v_readfirstlane_b32 s32, v19
	s_cmpk_lt_i32 s2, 0x200
	v_readfirstlane_b32 s19, v141
	s_waitcnt lgkmcnt(0)
	s_barrier
	s_cbranch_scc0 .LBB0_1302
	s_ashr_i32 s22, s2, 31
	s_lshr_b32 s12, s22, 29
	s_add_i32 s18, s2, s12
	s_and_b32 s12, s18, -8
	s_sub_i32 s16, s2, s12
	s_cmp_gt_i32 s16, -1
	s_cbranch_scc0 .LBB0_1279
	s_lshl_b32 s17, s16, 6
	s_ashr_i32 s12, s18, 3
	s_cbranch_execz .LBB0_1280
	s_branch .LBB0_1281

.LBB0_1302:
	s_waitcnt vmcnt(0)
	s_barrier
	s_and_saveexec_b64 s[4:5], s[92:93]
	s_cbranch_execz .LBB0_1354
	s_add_u32 s12, s88, 0x4000
	s_addc_u32 s13, s89, 0
	v_mov_b32_e32 v0, 0
	s_and_b32 s0, s2, 7
	s_lshl_b32 s0, s0, 7
	v_mov_b32_e32 v3, s0
	v_mov_b32_e32 v4, 1
	s_cmp_lg_u32 s32, 0
	s_cbranch_scc1 .Lgb6_slow
	global_atomic_add v3, v4, s[12:13] offset:2048
	buffer_inv sc1
	s_mov_b32 s0, 0
